# v58 plus diff-attention item epilogue: the two leftover vmcnt waits in front of the LDS exchange reads removed (they only waited on the next item's prefetch DMAs)
# speedup vs baseline: 1.0084x; 1.0007x over previous
; __device__ __forceinline__ int diff_item(ldsp lds, int qt, int bh, bool pre, unsigned* nctr, const bf16* U, bf16* O, const float* subw, float lam, float omlinit, float M0, int wave, int lane) {
;     ...
;     if (c == 0) { const float inv = 1.0f / l; float ssq = 0.f;
; #pragma unroll
;         for (int et = 0; et < 4; ++et)
; #pragma unroll
;             for (int i = 0; i < 16; ++i) { const float d = o[et][i] * inv - xp[(et * 16 + i) * 64 + lane_e]; o[et][i] = d; ssq += d * d; }
;         ssq += shx(ssq, 32);
;         const float rs = omlinit / sqrtf(ssq * (1.0f / 128.0f) + EPS);
.LBB0_822:
	s_waitcnt lgkmcnt(0)
	s_barrier
	s_andn2_b64 vcc, exec, s[36:37]
	s_cbranch_vccnz .LBB0_804
	v_div_scale_f32 v2, s[14:15], v1, v1, 1.0
	v_rcp_f32_e32 v3, v2
	s_nop 0
	v_fma_f32 v4, -v2, v3, 1.0
	v_fmac_f32_e32 v3, v4, v3
	v_div_scale_f32 v4, vcc, 1.0, v1, 1.0
	v_mul_f32_e32 v5, v4, v3
	v_fma_f32 v6, -v2, v5, v4
	v_fmac_f32_e32 v5, v6, v3
	v_fma_f32 v2, -v2, v5, v4
	v_div_fmas_f32 v2, v2, v3, v5
	v_div_fixup_f32 v14, v2, v1, 1.0
	v_lshl_add_u32 v1, v0, 2, s96
	s_nop 0
	ds_read2st64_b32 v[134:135], v1 offset1:1
	ds_read2st64_b32 v[136:137], v1 offset0:2 offset1:3
	ds_read2st64_b32 v[138:139], v1 offset0:4 offset1:5
	ds_read2st64_b32 v[140:141], v1 offset0:6 offset1:7
	ds_read2st64_b32 v[62:63], v1 offset0:8 offset1:9
	ds_read2st64_b32 v[142:143], v1 offset0:10 offset1:11
	ds_read2st64_b32 v[54:55], v1 offset0:12 offset1:13
	ds_read2st64_b32 v[132:133], v1 offset0:14 offset1:15
	ds_read2st64_b32 v[48:49], v1 offset0:16 offset1:17
	ds_read2st64_b32 v[60:61], v1 offset0:18 offset1:19
	ds_read2st64_b32 v[44:45], v1 offset0:20 offset1:21
	ds_read2st64_b32 v[52:53], v1 offset0:22 offset1:23
	ds_read2st64_b32 v[42:43], v1 offset0:24 offset1:25
	ds_read2st64_b32 v[50:51], v1 offset0:26 offset1:27
	ds_read2st64_b32 v[36:37], v1 offset0:28 offset1:29
	ds_read2st64_b32 v[46:47], v1 offset0:30 offset1:31
	ds_read2st64_b32 v[30:31], v1 offset0:32 offset1:33
	ds_read2st64_b32 v[40:41], v1 offset0:34 offset1:35
	ds_read2st64_b32 v[26:27], v1 offset0:36 offset1:37
	ds_read2st64_b32 v[34:35], v1 offset0:38 offset1:39
	ds_read2st64_b32 v[24:25], v1 offset0:40 offset1:41
	ds_read2st64_b32 v[32:33], v1 offset0:42 offset1:43
	ds_read2st64_b32 v[28:29], v1 offset0:44 offset1:45
	s_nop 0
	ds_read2st64_b32 v[128:129], v1 offset0:46 offset1:47
	ds_read2st64_b32 v[22:23], v1 offset0:48 offset1:49
	ds_read2st64_b32 v[20:21], v1 offset0:50 offset1:51
	ds_read2st64_b32 v[18:19], v1 offset0:52 offset1:53
	ds_read2st64_b32 v[16:17], v1 offset0:54 offset1:55
	ds_read2st64_b32 v[56:57], v1 offset0:56 offset1:57
	ds_read2st64_b32 v[2:3], v1 offset0:58 offset1:59
	s_waitcnt lgkmcnt(14)
	v_pk_fma_f32 v[116:117], v[116:117], v[14:15], v[138:139] op_sel_hi:[1,0,1] neg_lo:[0,0,1] neg_hi:[0,0,1]
	s_waitcnt lgkmcnt(7)
	v_pk_fma_f32 v[28:29], v[92:93], v[14:15], v[28:29] op_sel_hi:[1,0,1] neg_lo:[0,0,1] neg_hi:[0,0,1]
	s_waitcnt lgkmcnt(4)
	v_pk_fma_f32 v[20:21], v[66:67], v[14:15], v[20:21] op_sel_hi:[1,0,1] neg_lo:[0,0,1] neg_hi:[0,0,1]
	v_pk_fma_f32 v[22:23], v[64:65], v[14:15], v[22:23] op_sel_hi:[1,0,1] neg_lo:[0,0,1] neg_hi:[0,0,1]
	s_waitcnt lgkmcnt(0)
	v_pk_fma_f32 v[4:5], v[74:75], v[14:15], v[2:3] op_sel_hi:[1,0,1] neg_lo:[0,0,1] neg_hi:[0,0,1]
	ds_read2st64_b32 v[2:3], v1 offset0:60 offset1:61
	v_pk_fma_f32 v[74:75], v[122:123], v[14:15], v[142:143] op_sel_hi:[1,0,1] neg_lo:[0,0,1] neg_hi:[0,0,1]
	v_pk_fma_f32 v[16:17], v[70:71], v[14:15], v[16:17] op_sel_hi:[1,0,1] neg_lo:[0,0,1] neg_hi:[0,0,1]
	v_pk_fma_f32 v[18:19], v[68:69], v[14:15], v[18:19] op_sel_hi:[1,0,1] neg_lo:[0,0,1] neg_hi:[0,0,1]
	v_pk_mul_f32 v[138:139], v[116:117], v[116:117]
	s_waitcnt lgkmcnt(0)
	v_pk_fma_f32 v[6:7], v[76:77], v[14:15], v[2:3] op_sel_hi:[1,0,1] neg_lo:[0,0,1] neg_hi:[0,0,1]
	ds_read2st64_b32 v[2:3], v1 offset0:62 offset1:63
	v_pk_fma_f32 v[76:77], v[124:125], v[14:15], v[54:55] op_sel_hi:[1,0,1] neg_lo:[0,0,1] neg_hi:[0,0,1]
	v_pk_fma_f32 v[54:55], v[98:99], v[14:15], v[60:61] op_sel_hi:[1,0,1] neg_lo:[0,0,1] neg_hi:[0,0,1]
	v_pk_fma_f32 v[60:61], v[96:97], v[14:15], v[48:49] op_sel_hi:[1,0,1] neg_lo:[0,0,1] neg_hi:[0,0,1]
	v_pk_fma_f32 v[48:49], v[102:103], v[14:15], v[52:53] op_sel_hi:[1,0,1] neg_lo:[0,0,1] neg_hi:[0,0,1]
	s_waitcnt lgkmcnt(0)
	v_pk_fma_f32 v[8:9], v[78:79], v[14:15], v[2:3] op_sel_hi:[1,0,1] neg_lo:[0,0,1] neg_hi:[0,0,1]
	v_pk_fma_f32 v[78:79], v[114:115], v[14:15], v[136:137] op_sel_hi:[1,0,1] neg_lo:[0,0,1] neg_hi:[0,0,1]
	v_pk_fma_f32 v[114:115], v[112:113], v[14:15], v[134:135] op_sel_hi:[1,0,1] neg_lo:[0,0,1] neg_hi:[0,0,1]
	v_pk_mul_f32 v[136:137], v[78:79], v[78:79]
	v_pk_mul_f32 v[134:135], v[114:115], v[114:115]
	v_pk_fma_f32 v[112:113], v[118:119], v[14:15], v[140:141] op_sel_hi:[1,0,1] neg_lo:[0,0,1] neg_hi:[0,0,1]
	v_pk_fma_f32 v[118:119], v[120:121], v[14:15], v[62:63] op_sel_hi:[1,0,1] neg_lo:[0,0,1] neg_hi:[0,0,1]
	v_pk_fma_f32 v[62:63], v[126:127], v[14:15], v[132:133] op_sel_hi:[1,0,1] neg_lo:[0,0,1] neg_hi:[0,0,1]
	v_pk_fma_f32 v[52:53], v[100:101], v[14:15], v[44:45] op_sel_hi:[1,0,1] neg_lo:[0,0,1] neg_hi:[0,0,1]
	v_pk_fma_f32 v[44:45], v[106:107], v[14:15], v[50:51] op_sel_hi:[1,0,1] neg_lo:[0,0,1] neg_hi:[0,0,1]
	v_pk_fma_f32 v[50:51], v[104:105], v[14:15], v[42:43] op_sel_hi:[1,0,1] neg_lo:[0,0,1] neg_hi:[0,0,1]
	v_pk_fma_f32 v[42:43], v[110:111], v[14:15], v[46:47] op_sel_hi:[1,0,1] neg_lo:[0,0,1] neg_hi:[0,0,1]
	v_pk_fma_f32 v[46:47], v[108:109], v[14:15], v[36:37] op_sel_hi:[1,0,1] neg_lo:[0,0,1] neg_hi:[0,0,1]
	v_pk_fma_f32 v[36:37], v[82:83], v[14:15], v[40:41] op_sel_hi:[1,0,1] neg_lo:[0,0,1] neg_hi:[0,0,1]
	v_pk_fma_f32 v[40:41], v[80:81], v[14:15], v[30:31] op_sel_hi:[1,0,1] neg_lo:[0,0,1] neg_hi:[0,0,1]
	v_pk_fma_f32 v[30:31], v[86:87], v[14:15], v[34:35] op_sel_hi:[1,0,1] neg_lo:[0,0,1] neg_hi:[0,0,1]
	v_pk_fma_f32 v[34:35], v[84:85], v[14:15], v[26:27] op_sel_hi:[1,0,1] neg_lo:[0,0,1] neg_hi:[0,0,1]
	v_pk_fma_f32 v[26:27], v[90:91], v[14:15], v[32:33] op_sel_hi:[1,0,1] neg_lo:[0,0,1] neg_hi:[0,0,1]
	v_pk_fma_f32 v[32:33], v[88:89], v[14:15], v[24:25] op_sel_hi:[1,0,1] neg_lo:[0,0,1] neg_hi:[0,0,1]
	v_pk_fma_f32 v[24:25], v[94:95], v[14:15], v[128:129] op_sel_hi:[1,0,1] neg_lo:[0,0,1] neg_hi:[0,0,1]
	v_pk_fma_f32 v[14:15], v[72:73], v[14:15], v[56:57] op_sel_hi:[1,0,1] neg_lo:[0,0,1] neg_hi:[0,0,1]
	v_add_f32_e32 v72, v134, v135
	v_add_f32_e32 v72, v72, v136
	v_add_f32_e32 v72, v72, v137
	v_add_f32_e32 v72, v72, v138
	v_pk_mul_f32 v[140:141], v[112:113], v[112:113]
	v_add_f32_e32 v72, v72, v139
	v_add_f32_e32 v72, v72, v140
	v_pk_mul_f32 v[120:121], v[118:119], v[118:119]
	v_add_f32_e32 v72, v72, v141
	v_add_f32_e32 v72, v72, v120
	v_pk_mul_f32 v[122:123], v[74:75], v[74:75]
	v_add_f32_e32 v72, v72, v121
	v_add_f32_e32 v72, v72, v122
	v_pk_mul_f32 v[124:125], v[76:77], v[76:77]
	v_add_f32_e32 v72, v72, v123
	v_add_f32_e32 v72, v72, v124
	v_pk_mul_f32 v[126:127], v[62:63], v[62:63]
	v_add_f32_e32 v72, v72, v125
	v_add_f32_e32 v72, v72, v126
	v_mov_b32_e32 v1, v201
	v_and_or_b32 v2, v0, 31, s76
	v_mov_b32_e32 v3, s77
	v_pk_mul_f32 v[96:97], v[60:61], v[60:61]
	v_add_f32_e32 v72, v72, v127
	v_lshlrev_b64 v[2:3], 11, v[2:3]
	v_ashrrev_i32_e32 v0, 3, v0
	v_add_f32_e32 v72, v72, v96
	v_lshlrev_b32_e32 v1, 2, v1
	v_lshl_add_u64 v[2:3], s[22:23], 0, v[2:3]
	v_and_b32_e32 v0, -4, v0
	v_pk_mul_f32 v[98:99], v[54:55], v[54:55]
	v_add_f32_e32 v72, v72, v97
	v_xor_b32_e32 v144, 0x80, v1
	v_lshl_add_u64 v[2:3], s[10:11], 1, v[2:3]
	v_ashrrev_i32_e32 v1, 31, v0
	s_load_dwordx2 s[10:11], s[46:47], 0x80
	v_add_f32_e32 v72, v72, v98
	s_waitcnt lgkmcnt(0)
; __device__ __forceinline__ unsigned cvtpk(float lo, float hi) { f32x2_t v = {lo, hi}; bf16x2_t b = __builtin_convertvector(v, bf16x2_t); return __builtin_bit_cast(unsigned, b); }
; __device__ __forceinline__ int diff_item(ldsp lds, int qt, int bh, bool pre, unsigned* nctr, const bf16* U, bf16* O, const float* subw, float lam, float omlinit, float M0, int wave, int lane) {
;     ...
;             for (int i = 0; i < 16; ++i) { const float d = o[et][i] * inv - xp[(et * 16 + i) * 64 + lane_e]; o[et][i] = d; ssq += d * d; }
;         ssq += shx(ssq, 32);
;         const float rs = omlinit / sqrtf(ssq * (1.0f / 128.0f) + EPS);
;         bf16* op = O + (tokbase + t0 + r_e) * D + h * 128 + 4 * hh_e;
;         const float* swp = subw; asm volatile("" : "+s"(swp));
; #pragma unroll
;         for (int et = 0; et < 4; ++et)
; #pragma unroll
;             for (int g4 = 0; g4 < 4; ++g4) { const int e0 = 32 * et + 8 * g4; const f32x4 w = *(const f32x4*)(swp + e0 + 4 * hh_e);
;                 v2u pk; pk.x = cvtpk(o[et][4 * g4] * rs * w[0], o[et][4 * g4 + 1] * rs * w[1]); pk.y = cvtpk(o[et][4 * g4 + 2] * rs * w[2], o[et][4 * g4 + 3] * rs * w[3]);
;                 *(v2u*)(op + e0) = pk; }
	v_pk_mul_f32 v[100:101], v[52:53], v[52:53]
	v_lshlrev_b32_e32 v12, 2, v0
	v_add_u32_e32 v12, 0x20080, v12
	v_add_f32_e32 v72, v72, v99
	v_lshl_add_u64 v[10:11], v[0:1], 1, v[2:3]
	ds_read_b128 v[0:3], v12
	v_add_f32_e32 v72, v72, v100
	v_pk_mul_f32 v[102:103], v[48:49], v[48:49]
	v_add_f32_e32 v72, v72, v101
	v_add_f32_e32 v72, v72, v102
	v_pk_mul_f32 v[104:105], v[50:51], v[50:51]
	v_add_f32_e32 v72, v72, v103
	v_add_f32_e32 v72, v72, v104
	v_pk_mul_f32 v[106:107], v[44:45], v[44:45]
	v_add_f32_e32 v72, v72, v105
	v_add_f32_e32 v72, v72, v106
	v_pk_mul_f32 v[108:109], v[46:47], v[46:47]
	v_add_f32_e32 v72, v72, v107
	v_add_f32_e32 v72, v72, v108
	v_pk_mul_f32 v[110:111], v[42:43], v[42:43]
	v_add_f32_e32 v72, v72, v109
	v_add_f32_e32 v72, v72, v110
	v_pk_mul_f32 v[80:81], v[40:41], v[40:41]
	v_add_f32_e32 v72, v72, v111
	v_add_f32_e32 v72, v72, v80
	v_pk_mul_f32 v[82:83], v[36:37], v[36:37]
	v_add_f32_e32 v72, v72, v81
	v_add_f32_e32 v72, v72, v82
	v_pk_mul_f32 v[84:85], v[34:35], v[34:35]
	v_add_f32_e32 v72, v72, v83
	v_add_f32_e32 v72, v72, v84
	v_pk_mul_f32 v[86:87], v[30:31], v[30:31]
	v_add_f32_e32 v72, v72, v85
	v_add_f32_e32 v72, v72, v86
	v_pk_mul_f32 v[88:89], v[32:33], v[32:33]
	v_add_f32_e32 v72, v72, v87
	v_add_f32_e32 v72, v72, v88
	v_pk_mul_f32 v[90:91], v[26:27], v[26:27]
	v_add_f32_e32 v72, v72, v89
	v_add_f32_e32 v72, v72, v90
	v_pk_mul_f32 v[92:93], v[28:29], v[28:29]
	v_add_f32_e32 v72, v72, v91
	v_add_f32_e32 v72, v72, v92
	v_pk_mul_f32 v[94:95], v[24:25], v[24:25]
	v_add_f32_e32 v72, v72, v93
	v_add_f32_e32 v72, v72, v94
	v_pk_mul_f32 v[64:65], v[22:23], v[22:23]
	v_add_f32_e32 v72, v72, v95
	v_add_f32_e32 v64, v72, v64
	v_pk_mul_f32 v[66:67], v[20:21], v[20:21]
	v_add_f32_e32 v64, v64, v65
	v_add_f32_e32 v64, v64, v66
	v_pk_mul_f32 v[68:69], v[18:19], v[18:19]
	v_add_f32_e32 v64, v64, v67
	v_add_f32_e32 v64, v64, v68
	v_pk_mul_f32 v[70:71], v[16:17], v[16:17]
	v_add_f32_e32 v64, v64, v69
	v_add_f32_e32 v64, v64, v70
	v_pk_mul_f32 v[56:57], v[14:15], v[14:15]
	v_add_f32_e32 v64, v64, v71
	v_add_f32_e32 v56, v64, v56
	v_pk_mul_f32 v[38:39], v[4:5], v[4:5]
	v_add_f32_e32 v56, v56, v57
	v_add_f32_e32 v38, v56, v38
	v_pk_mul_f32 v[58:59], v[6:7], v[6:7]
	v_add_f32_e32 v38, v38, v39
	v_add_f32_e32 v38, v38, v58
	v_pk_mul_f32 v[130:131], v[8:9], v[8:9]
	v_add_f32_e32 v38, v38, v59
	v_add_f32_e32 v38, v38, v130
	v_add_f32_e32 v38, v38, v131
	ds_bpermute_b32 v39, v144, v38
	s_mov_b32 s10, 0xf800000
	s_waitcnt lgkmcnt(0)
	v_add_f32_e32 v38, v38, v39
	v_fmamk_f32 v38, v38, 0x3c000000, v209
	v_cmp_gt_f32_e32 vcc, s10, v38
	v_mul_f32_e32 v39, 0x4f800000, v38
	s_nop 0
	v_cndmask_b32_e32 v38, v38, v39, vcc
	v_sqrt_f32_e32 v39, v38
	s_nop 0
	v_add_u32_e32 v56, -1, v39
	v_fma_f32 v57, -v56, v39, v38
	v_cmp_ge_f32_e64 s[10:11], 0, v57
	v_add_u32_e32 v57, 1, v39
	s_nop 0
	v_cndmask_b32_e64 v56, v39, v56, s[10:11]
	v_fma_f32 v39, -v57, v39, v38
	v_cmp_lt_f32_e64 s[10:11], 0, v39
	s_nop 1
	v_cndmask_b32_e64 v39, v56, v57, s[10:11]
	v_mul_f32_e32 v56, 0x37800000, v39
	v_cndmask_b32_e32 v39, v39, v56, vcc
	v_cmp_class_f32_e32 vcc, v38, v210
	s_nop 1
	v_cndmask_b32_e32 v38, v39, v38, vcc
	v_div_scale_f32 v39, s[10:11], v38, v38, s33
	v_rcp_f32_e32 v56, v39
	s_nop 0
	v_fma_f32 v57, -v39, v56, 1.0
	v_fmac_f32_e32 v56, v57, v56
	v_div_scale_f32 v57, vcc, s33, v38, s33
	v_mul_f32_e32 v58, v57, v56
	v_fma_f32 v59, -v39, v58, v57
	v_fmac_f32_e32 v58, v59, v56
	v_fma_f32 v39, -v39, v58, v57
	v_div_fmas_f32 v39, v39, v56, v58
	v_div_fixup_f32 v38, v39, v38, s33
	v_pk_mul_f32 v[56:57], v[114:115], v[38:39] op_sel_hi:[1,0]
	v_pk_mul_f32 v[54:55], v[54:55], v[38:39] op_sel_hi:[1,0]
	s_waitcnt lgkmcnt(0)
	v_pk_mul_f32 v[0:1], v[0:1], v[56:57]
	v_pk_mul_f32 v[56:57], v[78:79], v[38:39] op_sel_hi:[1,0]
	v_cvt_pk_bf16_f32 v0, v0, v1
	v_pk_mul_f32 v[2:3], v[2:3], v[56:57]
	v_pk_mul_f32 v[56:57], v[116:117], v[38:39] op_sel_hi:[1,0]
	v_cvt_pk_bf16_f32 v1, v2, v3
	global_store_dwordx2 v[10:11], v[0:1], off
	ds_read_b128 v[0:3], v12 offset:32
	v_pk_mul_f32 v[52:53], v[52:53], v[38:39] op_sel_hi:[1,0]
	v_pk_mul_f32 v[48:49], v[48:49], v[38:39] op_sel_hi:[1,0]
	v_pk_mul_f32 v[44:45], v[44:45], v[38:39] op_sel_hi:[1,0]
	v_pk_mul_f32 v[42:43], v[42:43], v[38:39] op_sel_hi:[1,0]
	v_pk_mul_f32 v[40:41], v[40:41], v[38:39] op_sel_hi:[1,0]
	v_pk_mul_f32 v[36:37], v[36:37], v[38:39] op_sel_hi:[1,0]
	v_pk_mul_f32 v[34:35], v[34:35], v[38:39] op_sel_hi:[1,0]
	v_pk_mul_f32 v[30:31], v[30:31], v[38:39] op_sel_hi:[1,0]
	v_pk_mul_f32 v[26:27], v[26:27], v[38:39] op_sel_hi:[1,0]
	v_pk_mul_f32 v[24:25], v[24:25], v[38:39] op_sel_hi:[1,0]
	v_pk_mul_f32 v[22:23], v[22:23], v[38:39] op_sel_hi:[1,0]
	v_pk_mul_f32 v[20:21], v[20:21], v[38:39] op_sel_hi:[1,0]
	v_pk_mul_f32 v[18:19], v[18:19], v[38:39] op_sel_hi:[1,0]
	v_pk_mul_f32 v[16:17], v[16:17], v[38:39] op_sel_hi:[1,0]
	v_pk_mul_f32 v[14:15], v[14:15], v[38:39] op_sel_hi:[1,0]
	v_pk_mul_f32 v[4:5], v[4:5], v[38:39] op_sel_hi:[1,0]
	s_waitcnt lgkmcnt(0)
; __device__ __forceinline__ unsigned cvtpk(float lo, float hi) { f32x2_t v = {lo, hi}; bf16x2_t b = __builtin_convertvector(v, bf16x2_t); return __builtin_bit_cast(unsigned, b); }
; __device__ __forceinline__ int diff_item(ldsp lds, int qt, int bh, bool pre, unsigned* nctr, const bf16* U, bf16* O, const float* subw, float lam, float omlinit, float M0, int wave, int lane) {
;     ...
;         for (int et = 0; et < 4; ++et)
; #pragma unroll
;             for (int g4 = 0; g4 < 4; ++g4) { const int e0 = 32 * et + 8 * g4; const f32x4 w = *(const f32x4*)(swp + e0 + 4 * hh_e);
;                 v2u pk; pk.x = cvtpk(o[et][4 * g4] * rs * w[0], o[et][4 * g4 + 1] * rs * w[1]); pk.y = cvtpk(o[et][4 * g4 + 2] * rs * w[2], o[et][4 * g4 + 3] * rs * w[3]);
;                 *(v2u*)(op + e0) = pk; }
	v_pk_mul_f32 v[0:1], v[0:1], v[56:57]
	v_pk_mul_f32 v[56:57], v[112:113], v[38:39] op_sel_hi:[1,0]
	v_cvt_pk_bf16_f32 v0, v0, v1
	v_pk_mul_f32 v[2:3], v[2:3], v[56:57]
	v_pk_mul_f32 v[56:57], v[118:119], v[38:39] op_sel_hi:[1,0]
	v_cvt_pk_bf16_f32 v1, v2, v3
	global_store_dwordx2 v[10:11], v[0:1], off offset:16
	ds_read_b128 v[0:3], v12 offset:64
	s_waitcnt lgkmcnt(0)
	v_pk_mul_f32 v[0:1], v[0:1], v[56:57]
	v_pk_mul_f32 v[56:57], v[74:75], v[38:39] op_sel_hi:[1,0]
	v_cvt_pk_bf16_f32 v0, v0, v1
	v_pk_mul_f32 v[2:3], v[2:3], v[56:57]
	v_pk_mul_f32 v[56:57], v[76:77], v[38:39] op_sel_hi:[1,0]
	v_cvt_pk_bf16_f32 v1, v2, v3
	global_store_dwordx2 v[10:11], v[0:1], off offset:32
	ds_read_b128 v[0:3], v12 offset:96
	s_waitcnt lgkmcnt(0)
	v_pk_mul_f32 v[0:1], v[56:57], v[0:1]
	v_pk_mul_f32 v[56:57], v[62:63], v[38:39] op_sel_hi:[1,0]
	v_cvt_pk_bf16_f32 v0, v0, v1
	v_pk_mul_f32 v[2:3], v[56:57], v[2:3]
	v_pk_mul_f32 v[56:57], v[60:61], v[38:39] op_sel_hi:[1,0]
	v_cvt_pk_bf16_f32 v1, v2, v3
	global_store_dwordx2 v[10:11], v[0:1], off offset:48
	ds_read_b128 v[0:3], v12 offset:128
	s_waitcnt lgkmcnt(0)
	v_pk_mul_f32 v[0:1], v[56:57], v[0:1]
	v_pk_mul_f32 v[2:3], v[54:55], v[2:3]
	v_cvt_pk_bf16_f32 v0, v0, v1
	v_cvt_pk_bf16_f32 v1, v2, v3
	global_store_dwordx2 v[10:11], v[0:1], off offset:64
	ds_read_b128 v[0:3], v12 offset:160
	s_waitcnt lgkmcnt(0)
	v_pk_mul_f32 v[0:1], v[52:53], v[0:1]
	v_pk_mul_f32 v[2:3], v[48:49], v[2:3]
	v_cvt_pk_bf16_f32 v0, v0, v1
	v_cvt_pk_bf16_f32 v1, v2, v3
	global_store_dwordx2 v[10:11], v[0:1], off offset:80
	ds_read_b128 v[0:3], v12 offset:192
	v_pk_mul_f32 v[48:49], v[50:51], v[38:39] op_sel_hi:[1,0]
	s_waitcnt lgkmcnt(0)
	v_pk_mul_f32 v[2:3], v[44:45], v[2:3]
	v_pk_mul_f32 v[0:1], v[48:49], v[0:1]
	v_pk_mul_f32 v[44:45], v[46:47], v[38:39] op_sel_hi:[1,0]
	v_cvt_pk_bf16_f32 v0, v0, v1
	v_cvt_pk_bf16_f32 v1, v2, v3
	global_store_dwordx2 v[10:11], v[0:1], off offset:96
	ds_read_b128 v[0:3], v12 offset:224
	s_waitcnt lgkmcnt(0)
	v_pk_mul_f32 v[0:1], v[44:45], v[0:1]
	v_pk_mul_f32 v[2:3], v[42:43], v[2:3]
	v_cvt_pk_bf16_f32 v0, v0, v1
	v_cvt_pk_bf16_f32 v1, v2, v3
	global_store_dwordx2 v[10:11], v[0:1], off offset:112
	ds_read_b128 v[0:3], v12 offset:256
	s_waitcnt lgkmcnt(0)
	v_pk_mul_f32 v[0:1], v[40:41], v[0:1]
	v_pk_mul_f32 v[2:3], v[36:37], v[2:3]
	v_cvt_pk_bf16_f32 v0, v0, v1
	v_cvt_pk_bf16_f32 v1, v2, v3
	global_store_dwordx2 v[10:11], v[0:1], off offset:128
	ds_read_b128 v[0:3], v12 offset:288
	s_waitcnt lgkmcnt(0)
	v_pk_mul_f32 v[0:1], v[34:35], v[0:1]
	v_pk_mul_f32 v[2:3], v[30:31], v[2:3]
	v_cvt_pk_bf16_f32 v0, v0, v1
	v_cvt_pk_bf16_f32 v1, v2, v3
	global_store_dwordx2 v[10:11], v[0:1], off offset:144
	ds_read_b128 v[0:3], v12 offset:320
	v_pk_mul_f32 v[30:31], v[32:33], v[38:39] op_sel_hi:[1,0]
	s_waitcnt lgkmcnt(0)
	v_pk_mul_f32 v[2:3], v[26:27], v[2:3]
	v_pk_mul_f32 v[0:1], v[30:31], v[0:1]
	v_pk_mul_f32 v[26:27], v[28:29], v[38:39] op_sel_hi:[1,0]
	v_cvt_pk_bf16_f32 v0, v0, v1
	v_cvt_pk_bf16_f32 v1, v2, v3
	global_store_dwordx2 v[10:11], v[0:1], off offset:160
	ds_read_b128 v[0:3], v12 offset:352
	s_waitcnt lgkmcnt(0)
	v_pk_mul_f32 v[0:1], v[26:27], v[0:1]
	v_pk_mul_f32 v[2:3], v[24:25], v[2:3]
	v_cvt_pk_bf16_f32 v0, v0, v1
	v_cvt_pk_bf16_f32 v1, v2, v3
	global_store_dwordx2 v[10:11], v[0:1], off offset:176
	ds_read_b128 v[0:3], v12 offset:384
	s_waitcnt lgkmcnt(0)
	v_pk_mul_f32 v[0:1], v[22:23], v[0:1]
	v_pk_mul_f32 v[2:3], v[20:21], v[2:3]
	v_cvt_pk_bf16_f32 v0, v0, v1
	v_cvt_pk_bf16_f32 v1, v2, v3
	global_store_dwordx2 v[10:11], v[0:1], off offset:192
	ds_read_b128 v[0:3], v12 offset:416
	s_waitcnt lgkmcnt(0)
	v_pk_mul_f32 v[0:1], v[18:19], v[0:1]
	v_pk_mul_f32 v[2:3], v[16:17], v[2:3]
	v_cvt_pk_bf16_f32 v0, v0, v1
	v_cvt_pk_bf16_f32 v1, v2, v3
	global_store_dwordx2 v[10:11], v[0:1], off offset:208
	ds_read_b128 v[0:3], v12 offset:448
	s_waitcnt lgkmcnt(0)
	v_pk_mul_f32 v[0:1], v[14:15], v[0:1]
	v_pk_mul_f32 v[2:3], v[4:5], v[2:3]
	v_cvt_pk_bf16_f32 v0, v0, v1
	v_cvt_pk_bf16_f32 v1, v2, v3
	global_store_dwordx2 v[10:11], v[0:1], off offset:224
	ds_read_b128 v[0:3], v12 offset:480
	v_pk_mul_f32 v[4:5], v[6:7], v[38:39] op_sel_hi:[1,0]
	s_waitcnt lgkmcnt(0)
	v_pk_mul_f32 v[0:1], v[4:5], v[0:1]
	v_pk_mul_f32 v[4:5], v[8:9], v[38:39] op_sel_hi:[1,0]
	v_cvt_pk_bf16_f32 v0, v0, v1
	v_pk_mul_f32 v[2:3], v[4:5], v[2:3]
	s_nop 0
	v_cvt_pk_bf16_f32 v1, v2, v3
	global_store_dwordx2 v[10:11], v[0:1], off offset:240
	s_branch .LBB0_804

; __device__ __forceinline__ int diff_item(ldsp lds, int qt, int bh, bool pre, unsigned* nctr, const bf16* U, bf16* O, const float* subw, float lam, float omlinit, float M0, int wave, int lane) {
;     ...
;     if (c == 0) { const float inv = 1.0f / l; float ssq = 0.f;
; #pragma unroll
;         for (int et = 0; et < 4; ++et)
; #pragma unroll
;             for (int i = 0; i < 16; ++i) { const float d = o[et][i] * inv - xp[(et * 16 + i) * 64 + lane_e]; o[et][i] = d; ssq += d * d; }
;         ssq += shx(ssq, 32);
;         const float rs = omlinit / sqrtf(ssq * (1.0f / 128.0f) + EPS);
.LBB0_1866:
	s_waitcnt lgkmcnt(0)
	s_barrier
	s_andn2_b64 vcc, exec, s[36:37]
	s_cbranch_vccnz .LBB0_1848
	v_div_scale_f32 v2, s[4:5], v1, v1, 1.0
	v_rcp_f32_e32 v3, v2
	s_mov_b64 s[4:5], s[24:25]
	v_fma_f32 v4, -v2, v3, 1.0
	v_fmac_f32_e32 v3, v4, v3
	v_div_scale_f32 v4, vcc, 1.0, v1, 1.0
	v_mul_f32_e32 v5, v4, v3
	v_fma_f32 v6, -v2, v5, v4
	v_fmac_f32_e32 v5, v6, v3
	v_fma_f32 v2, -v2, v5, v4
	v_div_fmas_f32 v2, v2, v3, v5
	v_div_fixup_f32 v14, v2, v1, 1.0
	v_lshl_add_u32 v1, v0, 2, s96
	ds_read2st64_b32 v[60:61], v1 offset1:1
	ds_read2st64_b32 v[62:63], v1 offset0:2 offset1:3
	s_nop 0
	ds_read2st64_b32 v[132:133], v1 offset0:4 offset1:5
	ds_read2st64_b32 v[134:135], v1 offset0:6 offset1:7
	ds_read2st64_b32 v[136:137], v1 offset0:8 offset1:9
	ds_read2st64_b32 v[138:139], v1 offset0:10 offset1:11
	ds_read2st64_b32 v[54:55], v1 offset0:12 offset1:13
	ds_read2st64_b32 v[140:141], v1 offset0:14 offset1:15
	ds_read2st64_b32 v[48:49], v1 offset0:16 offset1:17
	ds_read2st64_b32 v[142:143], v1 offset0:18 offset1:19
	ds_read2st64_b32 v[44:45], v1 offset0:20 offset1:21
	ds_read2st64_b32 v[52:53], v1 offset0:22 offset1:23
	ds_read2st64_b32 v[42:43], v1 offset0:24 offset1:25
	ds_read2st64_b32 v[50:51], v1 offset0:26 offset1:27
	ds_read2st64_b32 v[36:37], v1 offset0:28 offset1:29
	ds_read2st64_b32 v[46:47], v1 offset0:30 offset1:31
	ds_read2st64_b32 v[30:31], v1 offset0:32 offset1:33
	ds_read2st64_b32 v[40:41], v1 offset0:34 offset1:35
	ds_read2st64_b32 v[26:27], v1 offset0:36 offset1:37
	ds_read2st64_b32 v[34:35], v1 offset0:38 offset1:39
	ds_read2st64_b32 v[24:25], v1 offset0:40 offset1:41
	ds_read2st64_b32 v[32:33], v1 offset0:42 offset1:43
	ds_read2st64_b32 v[28:29], v1 offset0:44 offset1:45
	s_nop 0
	ds_read2st64_b32 v[128:129], v1 offset0:46 offset1:47
	ds_read2st64_b32 v[22:23], v1 offset0:48 offset1:49
	ds_read2st64_b32 v[20:21], v1 offset0:50 offset1:51
	ds_read2st64_b32 v[18:19], v1 offset0:52 offset1:53
	ds_read2st64_b32 v[16:17], v1 offset0:54 offset1:55
	ds_read2st64_b32 v[56:57], v1 offset0:56 offset1:57
	ds_read2st64_b32 v[2:3], v1 offset0:58 offset1:59
	s_waitcnt lgkmcnt(14)
	v_pk_fma_f32 v[116:117], v[116:117], v[14:15], v[132:133] op_sel_hi:[1,0,1] neg_lo:[0,0,1] neg_hi:[0,0,1]
	s_waitcnt lgkmcnt(7)
	v_pk_fma_f32 v[28:29], v[92:93], v[14:15], v[28:29] op_sel_hi:[1,0,1] neg_lo:[0,0,1] neg_hi:[0,0,1]
	s_waitcnt lgkmcnt(4)
	v_pk_fma_f32 v[20:21], v[66:67], v[14:15], v[20:21] op_sel_hi:[1,0,1] neg_lo:[0,0,1] neg_hi:[0,0,1]
	v_pk_fma_f32 v[22:23], v[64:65], v[14:15], v[22:23] op_sel_hi:[1,0,1] neg_lo:[0,0,1] neg_hi:[0,0,1]
	s_waitcnt lgkmcnt(0)
	v_pk_fma_f32 v[4:5], v[74:75], v[14:15], v[2:3] op_sel_hi:[1,0,1] neg_lo:[0,0,1] neg_hi:[0,0,1]
	ds_read2st64_b32 v[2:3], v1 offset0:60 offset1:61
	v_pk_fma_f32 v[74:75], v[122:123], v[14:15], v[138:139] op_sel_hi:[1,0,1] neg_lo:[0,0,1] neg_hi:[0,0,1]
	v_pk_fma_f32 v[16:17], v[70:71], v[14:15], v[16:17] op_sel_hi:[1,0,1] neg_lo:[0,0,1] neg_hi:[0,0,1]
	v_pk_fma_f32 v[18:19], v[68:69], v[14:15], v[18:19] op_sel_hi:[1,0,1] neg_lo:[0,0,1] neg_hi:[0,0,1]
	v_pk_mul_f32 v[132:133], v[116:117], v[116:117]
	s_waitcnt lgkmcnt(0)
	v_pk_fma_f32 v[6:7], v[76:77], v[14:15], v[2:3] op_sel_hi:[1,0,1] neg_lo:[0,0,1] neg_hi:[0,0,1]
	ds_read2st64_b32 v[2:3], v1 offset0:62 offset1:63
	v_pk_fma_f32 v[76:77], v[124:125], v[14:15], v[54:55] op_sel_hi:[1,0,1] neg_lo:[0,0,1] neg_hi:[0,0,1]
	v_pk_fma_f32 v[54:55], v[98:99], v[14:15], v[142:143] op_sel_hi:[1,0,1] neg_lo:[0,0,1] neg_hi:[0,0,1]
	v_pk_mul_f32 v[122:123], v[74:75], v[74:75]
	v_pk_mul_f32 v[124:125], v[76:77], v[76:77]
	s_waitcnt lgkmcnt(0)
	v_pk_fma_f32 v[8:9], v[78:79], v[14:15], v[2:3] op_sel_hi:[1,0,1] neg_lo:[0,0,1] neg_hi:[0,0,1]
	v_pk_fma_f32 v[78:79], v[114:115], v[14:15], v[62:63] op_sel_hi:[1,0,1] neg_lo:[0,0,1] neg_hi:[0,0,1]
	v_pk_fma_f32 v[114:115], v[112:113], v[14:15], v[60:61] op_sel_hi:[1,0,1] neg_lo:[0,0,1] neg_hi:[0,0,1]
	v_pk_mul_f32 v[144:145], v[78:79], v[78:79]
	v_pk_mul_f32 v[146:147], v[114:115], v[114:115]
	v_pk_fma_f32 v[112:113], v[118:119], v[14:15], v[134:135] op_sel_hi:[1,0,1] neg_lo:[0,0,1] neg_hi:[0,0,1]
	v_pk_fma_f32 v[118:119], v[120:121], v[14:15], v[136:137] op_sel_hi:[1,0,1] neg_lo:[0,0,1] neg_hi:[0,0,1]
	v_pk_fma_f32 v[62:63], v[126:127], v[14:15], v[140:141] op_sel_hi:[1,0,1] neg_lo:[0,0,1] neg_hi:[0,0,1]
	v_pk_fma_f32 v[60:61], v[96:97], v[14:15], v[48:49] op_sel_hi:[1,0,1] neg_lo:[0,0,1] neg_hi:[0,0,1]
	v_pk_fma_f32 v[48:49], v[102:103], v[14:15], v[52:53] op_sel_hi:[1,0,1] neg_lo:[0,0,1] neg_hi:[0,0,1]
	v_pk_fma_f32 v[52:53], v[100:101], v[14:15], v[44:45] op_sel_hi:[1,0,1] neg_lo:[0,0,1] neg_hi:[0,0,1]
	v_pk_fma_f32 v[44:45], v[106:107], v[14:15], v[50:51] op_sel_hi:[1,0,1] neg_lo:[0,0,1] neg_hi:[0,0,1]
	v_pk_fma_f32 v[50:51], v[104:105], v[14:15], v[42:43] op_sel_hi:[1,0,1] neg_lo:[0,0,1] neg_hi:[0,0,1]
	v_pk_fma_f32 v[42:43], v[110:111], v[14:15], v[46:47] op_sel_hi:[1,0,1] neg_lo:[0,0,1] neg_hi:[0,0,1]
	v_pk_fma_f32 v[46:47], v[108:109], v[14:15], v[36:37] op_sel_hi:[1,0,1] neg_lo:[0,0,1] neg_hi:[0,0,1]
	v_pk_fma_f32 v[36:37], v[82:83], v[14:15], v[40:41] op_sel_hi:[1,0,1] neg_lo:[0,0,1] neg_hi:[0,0,1]
	v_pk_fma_f32 v[40:41], v[80:81], v[14:15], v[30:31] op_sel_hi:[1,0,1] neg_lo:[0,0,1] neg_hi:[0,0,1]
	v_pk_fma_f32 v[30:31], v[86:87], v[14:15], v[34:35] op_sel_hi:[1,0,1] neg_lo:[0,0,1] neg_hi:[0,0,1]
	v_pk_fma_f32 v[34:35], v[84:85], v[14:15], v[26:27] op_sel_hi:[1,0,1] neg_lo:[0,0,1] neg_hi:[0,0,1]
	v_pk_fma_f32 v[26:27], v[90:91], v[14:15], v[32:33] op_sel_hi:[1,0,1] neg_lo:[0,0,1] neg_hi:[0,0,1]
	v_pk_fma_f32 v[32:33], v[88:89], v[14:15], v[24:25] op_sel_hi:[1,0,1] neg_lo:[0,0,1] neg_hi:[0,0,1]
; __device__ __forceinline__ unsigned cvtpk(float lo, float hi) { f32x2_t v = {lo, hi}; bf16x2_t b = __builtin_convertvector(v, bf16x2_t); return __builtin_bit_cast(unsigned, b); }
; __device__ __forceinline__ int diff_item(ldsp lds, int qt, int bh, bool pre, unsigned* nctr, const bf16* U, bf16* O, const float* subw, float lam, float omlinit, float M0, int wave, int lane) {
;     ...
;             for (int i = 0; i < 16; ++i) { const float d = o[et][i] * inv - xp[(et * 16 + i) * 64 + lane_e]; o[et][i] = d; ssq += d * d; }
;         ssq += shx(ssq, 32);
;         const float rs = omlinit / sqrtf(ssq * (1.0f / 128.0f) + EPS);
;         bf16* op = O + (tokbase + t0 + r_e) * D + h * 128 + 4 * hh_e;
;         const float* swp = subw; asm volatile("" : "+s"(swp));
; #pragma unroll
;         for (int et = 0; et < 4; ++et)
; #pragma unroll
;             for (int g4 = 0; g4 < 4; ++g4) { const int e0 = 32 * et + 8 * g4; const f32x4 w = *(const f32x4*)(swp + e0 + 4 * hh_e);
;                 v2u pk; pk.x = cvtpk(o[et][4 * g4] * rs * w[0], o[et][4 * g4 + 1] * rs * w[1]); pk.y = cvtpk(o[et][4 * g4 + 2] * rs * w[2], o[et][4 * g4 + 3] * rs * w[3]);
;                 *(v2u*)(op + e0) = pk; }
	v_pk_fma_f32 v[24:25], v[94:95], v[14:15], v[128:129] op_sel_hi:[1,0,1] neg_lo:[0,0,1] neg_hi:[0,0,1]
	v_pk_fma_f32 v[14:15], v[72:73], v[14:15], v[56:57] op_sel_hi:[1,0,1] neg_lo:[0,0,1] neg_hi:[0,0,1]
	v_add_f32_e32 v72, v146, v147
	v_add_f32_e32 v72, v72, v144
	v_add_f32_e32 v72, v72, v145
	v_add_f32_e32 v72, v72, v132
	v_pk_mul_f32 v[134:135], v[112:113], v[112:113]
	v_add_f32_e32 v72, v72, v133
	v_add_f32_e32 v72, v72, v134
	v_pk_mul_f32 v[120:121], v[118:119], v[118:119]
	v_add_f32_e32 v72, v72, v135
	v_add_f32_e32 v72, v72, v120
	v_add_f32_e32 v72, v72, v121
	v_add_f32_e32 v72, v72, v122
	v_add_f32_e32 v72, v72, v123
	v_add_f32_e32 v72, v72, v124
	v_pk_mul_f32 v[126:127], v[62:63], v[62:63]
	v_add_f32_e32 v72, v72, v125
	v_add_f32_e32 v72, v72, v126
	v_mov_b32_e32 v1, v201
	v_pk_mul_f32 v[96:97], v[60:61], v[60:61]
	v_add_f32_e32 v72, v72, v127
	v_and_or_b32 v2, v0, 31, s78
	v_mov_b32_e32 v3, s79
	v_ashrrev_i32_e32 v0, 3, v0
	v_add_f32_e32 v72, v72, v96
	v_lshlrev_b32_e32 v1, 2, v1
	v_lshlrev_b64 v[2:3], 11, v[2:3]
	v_and_b32_e32 v0, -4, v0
	v_pk_mul_f32 v[98:99], v[54:55], v[54:55]
	v_add_f32_e32 v72, v72, v97
	v_xor_b32_e32 v148, 0x80, v1
	v_lshl_add_u64 v[2:3], s[20:21], 0, v[2:3]
	v_ashrrev_i32_e32 v1, 31, v0
	v_add_f32_e32 v72, v72, v98
	v_lshl_add_u64 v[2:3], s[16:17], 1, v[2:3]
	v_pk_mul_f32 v[100:101], v[52:53], v[52:53]
	v_lshlrev_b32_e32 v12, 2, v0
	v_add_u32_e32 v12, 0x20080, v12
	v_add_f32_e32 v72, v72, v99
	v_lshl_add_u64 v[10:11], v[0:1], 1, v[2:3]
	ds_read_b128 v[0:3], v12
	v_add_f32_e32 v72, v72, v100
	v_pk_mul_f32 v[102:103], v[48:49], v[48:49]
	v_add_f32_e32 v72, v72, v101
	v_add_f32_e32 v72, v72, v102
	v_pk_mul_f32 v[104:105], v[50:51], v[50:51]
	v_add_f32_e32 v72, v72, v103
	v_add_f32_e32 v72, v72, v104
	v_pk_mul_f32 v[106:107], v[44:45], v[44:45]
	v_add_f32_e32 v72, v72, v105
	v_add_f32_e32 v72, v72, v106
	v_pk_mul_f32 v[108:109], v[46:47], v[46:47]
	v_add_f32_e32 v72, v72, v107
	v_add_f32_e32 v72, v72, v108
	v_pk_mul_f32 v[110:111], v[42:43], v[42:43]
	v_add_f32_e32 v72, v72, v109
	v_add_f32_e32 v72, v72, v110
	v_pk_mul_f32 v[80:81], v[40:41], v[40:41]
	v_add_f32_e32 v72, v72, v111
	v_add_f32_e32 v72, v72, v80
	v_pk_mul_f32 v[82:83], v[36:37], v[36:37]
	v_add_f32_e32 v72, v72, v81
	v_add_f32_e32 v72, v72, v82
	v_pk_mul_f32 v[84:85], v[34:35], v[34:35]
	v_add_f32_e32 v72, v72, v83
	v_add_f32_e32 v72, v72, v84
	v_pk_mul_f32 v[86:87], v[30:31], v[30:31]
	v_add_f32_e32 v72, v72, v85
	v_add_f32_e32 v72, v72, v86
	v_pk_mul_f32 v[88:89], v[32:33], v[32:33]
	v_add_f32_e32 v72, v72, v87
	v_add_f32_e32 v72, v72, v88
	v_pk_mul_f32 v[90:91], v[26:27], v[26:27]
	v_add_f32_e32 v72, v72, v89
	v_add_f32_e32 v72, v72, v90
	v_pk_mul_f32 v[92:93], v[28:29], v[28:29]
	v_add_f32_e32 v72, v72, v91
	v_add_f32_e32 v72, v72, v92
	v_pk_mul_f32 v[94:95], v[24:25], v[24:25]
	v_add_f32_e32 v72, v72, v93
	v_add_f32_e32 v72, v72, v94
	v_pk_mul_f32 v[64:65], v[22:23], v[22:23]
	v_add_f32_e32 v72, v72, v95
	v_add_f32_e32 v64, v72, v64
	v_pk_mul_f32 v[66:67], v[20:21], v[20:21]
	v_add_f32_e32 v64, v64, v65
	v_add_f32_e32 v64, v64, v66
	v_pk_mul_f32 v[68:69], v[18:19], v[18:19]
	v_add_f32_e32 v64, v64, v67
	v_add_f32_e32 v64, v64, v68
	v_pk_mul_f32 v[70:71], v[16:17], v[16:17]
	v_add_f32_e32 v64, v64, v69
	v_add_f32_e32 v64, v64, v70
	v_pk_mul_f32 v[56:57], v[14:15], v[14:15]
	v_add_f32_e32 v64, v64, v71
	v_add_f32_e32 v56, v64, v56
	v_pk_mul_f32 v[38:39], v[4:5], v[4:5]
	v_add_f32_e32 v56, v56, v57
	v_add_f32_e32 v38, v56, v38
	v_pk_mul_f32 v[58:59], v[6:7], v[6:7]
	v_add_f32_e32 v38, v38, v39
	v_add_f32_e32 v38, v38, v58
	v_pk_mul_f32 v[130:131], v[8:9], v[8:9]
	v_add_f32_e32 v38, v38, v59
	v_add_f32_e32 v38, v38, v130
	v_add_f32_e32 v38, v38, v131
	ds_bpermute_b32 v39, v148, v38
	s_mov_b32 s4, 0xf800000
	s_waitcnt lgkmcnt(0)
	v_add_f32_e32 v38, v38, v39
	v_fmamk_f32 v38, v38, 0x3c000000, v209
	v_cmp_gt_f32_e32 vcc, s4, v38
	v_mul_f32_e32 v39, 0x4f800000, v38
	s_nop 0
	v_cndmask_b32_e32 v38, v38, v39, vcc
	v_sqrt_f32_e32 v39, v38
	s_nop 0
	v_add_u32_e32 v56, -1, v39
	v_fma_f32 v57, -v56, v39, v38
	v_cmp_ge_f32_e64 s[16:17], 0, v57
	v_add_u32_e32 v57, 1, v39
	s_nop 0
	v_cndmask_b32_e64 v56, v39, v56, s[16:17]
	v_fma_f32 v39, -v57, v39, v38
	v_cmp_lt_f32_e64 s[16:17], 0, v39
	s_nop 1
	v_cndmask_b32_e64 v39, v56, v57, s[16:17]
	v_mul_f32_e32 v56, 0x37800000, v39
	v_cndmask_b32_e32 v39, v39, v56, vcc
	v_cmp_class_f32_e32 vcc, v38, v210
	s_nop 1
	v_cndmask_b32_e32 v38, v39, v38, vcc
	v_div_scale_f32 v39, s[4:5], v38, v38, s13
	v_rcp_f32_e32 v56, v39
	s_nop 0
	v_fma_f32 v57, -v39, v56, 1.0
	v_fmac_f32_e32 v56, v57, v56
	v_div_scale_f32 v57, vcc, s13, v38, s13
	v_mul_f32_e32 v58, v57, v56
	v_fma_f32 v59, -v39, v58, v57
	v_fmac_f32_e32 v58, v59, v56
	v_fma_f32 v39, -v39, v58, v57
	v_div_fmas_f32 v39, v39, v56, v58
	v_div_fixup_f32 v38, v39, v38, s13
	v_pk_mul_f32 v[56:57], v[114:115], v[38:39] op_sel_hi:[1,0]
	v_pk_mul_f32 v[54:55], v[54:55], v[38:39] op_sel_hi:[1,0]
	s_waitcnt lgkmcnt(0)
; __device__ __forceinline__ unsigned cvtpk(float lo, float hi) { f32x2_t v = {lo, hi}; bf16x2_t b = __builtin_convertvector(v, bf16x2_t); return __builtin_bit_cast(unsigned, b); }
; __device__ __forceinline__ int diff_item(ldsp lds, int qt, int bh, bool pre, unsigned* nctr, const bf16* U, bf16* O, const float* subw, float lam, float omlinit, float M0, int wave, int lane) {
;     ...
;         for (int et = 0; et < 4; ++et)
; #pragma unroll
;             for (int g4 = 0; g4 < 4; ++g4) { const int e0 = 32 * et + 8 * g4; const f32x4 w = *(const f32x4*)(swp + e0 + 4 * hh_e);
;                 v2u pk; pk.x = cvtpk(o[et][4 * g4] * rs * w[0], o[et][4 * g4 + 1] * rs * w[1]); pk.y = cvtpk(o[et][4 * g4 + 2] * rs * w[2], o[et][4 * g4 + 3] * rs * w[3]);
;                 *(v2u*)(op + e0) = pk; }
	v_pk_mul_f32 v[0:1], v[0:1], v[56:57]
	v_pk_mul_f32 v[56:57], v[78:79], v[38:39] op_sel_hi:[1,0]
	v_cvt_pk_bf16_f32 v0, v0, v1
	v_pk_mul_f32 v[2:3], v[2:3], v[56:57]
	v_pk_mul_f32 v[56:57], v[116:117], v[38:39] op_sel_hi:[1,0]
	v_cvt_pk_bf16_f32 v1, v2, v3
	global_store_dwordx2 v[10:11], v[0:1], off
	ds_read_b128 v[0:3], v12 offset:32
	v_pk_mul_f32 v[52:53], v[52:53], v[38:39] op_sel_hi:[1,0]
	v_pk_mul_f32 v[48:49], v[48:49], v[38:39] op_sel_hi:[1,0]
	v_pk_mul_f32 v[44:45], v[44:45], v[38:39] op_sel_hi:[1,0]
	v_pk_mul_f32 v[42:43], v[42:43], v[38:39] op_sel_hi:[1,0]
	v_pk_mul_f32 v[40:41], v[40:41], v[38:39] op_sel_hi:[1,0]
	v_pk_mul_f32 v[36:37], v[36:37], v[38:39] op_sel_hi:[1,0]
	v_pk_mul_f32 v[34:35], v[34:35], v[38:39] op_sel_hi:[1,0]
	v_pk_mul_f32 v[30:31], v[30:31], v[38:39] op_sel_hi:[1,0]
	v_pk_mul_f32 v[26:27], v[26:27], v[38:39] op_sel_hi:[1,0]
	v_pk_mul_f32 v[24:25], v[24:25], v[38:39] op_sel_hi:[1,0]
	v_pk_mul_f32 v[22:23], v[22:23], v[38:39] op_sel_hi:[1,0]
	v_pk_mul_f32 v[20:21], v[20:21], v[38:39] op_sel_hi:[1,0]
	v_pk_mul_f32 v[18:19], v[18:19], v[38:39] op_sel_hi:[1,0]
	v_pk_mul_f32 v[16:17], v[16:17], v[38:39] op_sel_hi:[1,0]
	v_pk_mul_f32 v[14:15], v[14:15], v[38:39] op_sel_hi:[1,0]
	v_pk_mul_f32 v[4:5], v[4:5], v[38:39] op_sel_hi:[1,0]
	s_waitcnt lgkmcnt(0)
	v_pk_mul_f32 v[0:1], v[0:1], v[56:57]
	v_pk_mul_f32 v[56:57], v[112:113], v[38:39] op_sel_hi:[1,0]
	v_cvt_pk_bf16_f32 v0, v0, v1
	v_pk_mul_f32 v[2:3], v[2:3], v[56:57]
	v_pk_mul_f32 v[56:57], v[118:119], v[38:39] op_sel_hi:[1,0]
	v_cvt_pk_bf16_f32 v1, v2, v3
	global_store_dwordx2 v[10:11], v[0:1], off offset:16
	ds_read_b128 v[0:3], v12 offset:64
	s_waitcnt lgkmcnt(0)
	v_pk_mul_f32 v[0:1], v[0:1], v[56:57]
	v_pk_mul_f32 v[56:57], v[74:75], v[38:39] op_sel_hi:[1,0]
	v_cvt_pk_bf16_f32 v0, v0, v1
	v_pk_mul_f32 v[2:3], v[2:3], v[56:57]
	v_pk_mul_f32 v[56:57], v[76:77], v[38:39] op_sel_hi:[1,0]
	v_cvt_pk_bf16_f32 v1, v2, v3
	global_store_dwordx2 v[10:11], v[0:1], off offset:32
	ds_read_b128 v[0:3], v12 offset:96
	s_waitcnt lgkmcnt(0)
	v_pk_mul_f32 v[0:1], v[56:57], v[0:1]
	v_pk_mul_f32 v[56:57], v[62:63], v[38:39] op_sel_hi:[1,0]
	v_cvt_pk_bf16_f32 v0, v0, v1
	v_pk_mul_f32 v[2:3], v[56:57], v[2:3]
	v_pk_mul_f32 v[56:57], v[60:61], v[38:39] op_sel_hi:[1,0]
	v_cvt_pk_bf16_f32 v1, v2, v3
	global_store_dwordx2 v[10:11], v[0:1], off offset:48
	ds_read_b128 v[0:3], v12 offset:128
	s_waitcnt lgkmcnt(0)
	v_pk_mul_f32 v[0:1], v[56:57], v[0:1]
	v_pk_mul_f32 v[2:3], v[54:55], v[2:3]
	v_cvt_pk_bf16_f32 v0, v0, v1
	v_cvt_pk_bf16_f32 v1, v2, v3
	global_store_dwordx2 v[10:11], v[0:1], off offset:64
	ds_read_b128 v[0:3], v12 offset:160
	s_waitcnt lgkmcnt(0)
	v_pk_mul_f32 v[0:1], v[52:53], v[0:1]
	v_pk_mul_f32 v[2:3], v[48:49], v[2:3]
	v_cvt_pk_bf16_f32 v0, v0, v1
	v_cvt_pk_bf16_f32 v1, v2, v3
	global_store_dwordx2 v[10:11], v[0:1], off offset:80
	ds_read_b128 v[0:3], v12 offset:192
	v_pk_mul_f32 v[48:49], v[50:51], v[38:39] op_sel_hi:[1,0]
	s_waitcnt lgkmcnt(0)
	v_pk_mul_f32 v[2:3], v[44:45], v[2:3]
	v_pk_mul_f32 v[0:1], v[48:49], v[0:1]
	v_pk_mul_f32 v[44:45], v[46:47], v[38:39] op_sel_hi:[1,0]
	v_cvt_pk_bf16_f32 v0, v0, v1
	v_cvt_pk_bf16_f32 v1, v2, v3
	global_store_dwordx2 v[10:11], v[0:1], off offset:96
	ds_read_b128 v[0:3], v12 offset:224
	s_waitcnt lgkmcnt(0)
	v_pk_mul_f32 v[0:1], v[44:45], v[0:1]
	v_pk_mul_f32 v[2:3], v[42:43], v[2:3]
	v_cvt_pk_bf16_f32 v0, v0, v1
	v_cvt_pk_bf16_f32 v1, v2, v3
	global_store_dwordx2 v[10:11], v[0:1], off offset:112
	ds_read_b128 v[0:3], v12 offset:256
	s_waitcnt lgkmcnt(0)
	v_pk_mul_f32 v[0:1], v[40:41], v[0:1]
	v_pk_mul_f32 v[2:3], v[36:37], v[2:3]
	v_cvt_pk_bf16_f32 v0, v0, v1
	v_cvt_pk_bf16_f32 v1, v2, v3
	global_store_dwordx2 v[10:11], v[0:1], off offset:128
	ds_read_b128 v[0:3], v12 offset:288
	s_waitcnt lgkmcnt(0)
	v_pk_mul_f32 v[0:1], v[34:35], v[0:1]
	v_pk_mul_f32 v[2:3], v[30:31], v[2:3]
	v_cvt_pk_bf16_f32 v0, v0, v1
	v_cvt_pk_bf16_f32 v1, v2, v3
	global_store_dwordx2 v[10:11], v[0:1], off offset:144
	ds_read_b128 v[0:3], v12 offset:320
	v_pk_mul_f32 v[30:31], v[32:33], v[38:39] op_sel_hi:[1,0]
	s_waitcnt lgkmcnt(0)
	v_pk_mul_f32 v[2:3], v[26:27], v[2:3]
	v_pk_mul_f32 v[0:1], v[30:31], v[0:1]
	v_pk_mul_f32 v[26:27], v[28:29], v[38:39] op_sel_hi:[1,0]
	v_cvt_pk_bf16_f32 v0, v0, v1
	v_cvt_pk_bf16_f32 v1, v2, v3
	global_store_dwordx2 v[10:11], v[0:1], off offset:160
	ds_read_b128 v[0:3], v12 offset:352
	s_waitcnt lgkmcnt(0)
	v_pk_mul_f32 v[0:1], v[26:27], v[0:1]
	v_pk_mul_f32 v[2:3], v[24:25], v[2:3]
	v_cvt_pk_bf16_f32 v0, v0, v1
	v_cvt_pk_bf16_f32 v1, v2, v3
	global_store_dwordx2 v[10:11], v[0:1], off offset:176
	ds_read_b128 v[0:3], v12 offset:384
	s_waitcnt lgkmcnt(0)
	v_pk_mul_f32 v[0:1], v[22:23], v[0:1]
	v_pk_mul_f32 v[2:3], v[20:21], v[2:3]
	v_cvt_pk_bf16_f32 v0, v0, v1
	v_cvt_pk_bf16_f32 v1, v2, v3
	global_store_dwordx2 v[10:11], v[0:1], off offset:192
	ds_read_b128 v[0:3], v12 offset:416
	s_waitcnt lgkmcnt(0)
	v_pk_mul_f32 v[0:1], v[18:19], v[0:1]
	v_pk_mul_f32 v[2:3], v[16:17], v[2:3]
	v_cvt_pk_bf16_f32 v0, v0, v1
	v_cvt_pk_bf16_f32 v1, v2, v3
	global_store_dwordx2 v[10:11], v[0:1], off offset:208
	ds_read_b128 v[0:3], v12 offset:448
	s_waitcnt lgkmcnt(0)
	v_pk_mul_f32 v[0:1], v[14:15], v[0:1]
	v_pk_mul_f32 v[2:3], v[4:5], v[2:3]
	v_cvt_pk_bf16_f32 v0, v0, v1
	v_cvt_pk_bf16_f32 v1, v2, v3
	global_store_dwordx2 v[10:11], v[0:1], off offset:224
	ds_read_b128 v[0:3], v12 offset:480
	v_pk_mul_f32 v[4:5], v[6:7], v[38:39] op_sel_hi:[1,0]
	s_waitcnt lgkmcnt(0)
	v_pk_mul_f32 v[0:1], v[4:5], v[0:1]
	v_pk_mul_f32 v[4:5], v[8:9], v[38:39] op_sel_hi:[1,0]
	v_cvt_pk_bf16_f32 v0, v0, v1
	v_pk_mul_f32 v[2:3], v[4:5], v[2:3]
	s_nop 0
	v_cvt_pk_bf16_f32 v1, v2, v3
	global_store_dwordx2 v[10:11], v[0:1], off offset:240
	s_branch .LBB0_1848
